# GEMM accumulator zero-init with v_mov_b64 pairs instead of v_pk_mov_b32
# baseline (speedup 1.0000x reference)
.Lsw_done:
	s_ashr_i32 s21, s20, 31
	s_lshl_b64 s[14:15], s[20:21], 19
	s_add_u32 s14, s90, s14
	s_addc_u32 s15, s91, s15
	s_and_b64 s[16:17], s[44:45], exec
	s_cselect_b32 s21, s15, s23
	s_cselect_b32 s28, s14, s22
	s_ashr_i32 s19, s18, 31
	s_lshl_b64 s[16:17], s[18:19], 19
	s_add_u32 s16, s5, s16
	s_addc_u32 s17, s89, s17
	s_and_b64 s[26:27], s[44:45], exec
	s_cselect_b32 s19, s17, s25
	s_cselect_b32 s29, s16, s24
	s_add_u32 s22, s22, 0x40080
	s_addc_u32 s23, s23, 0
	s_add_u32 s30, s24, 0x100
	v_mov_b32_e32 v0, 0
	s_addc_u32 s31, s25, 0
	s_mov_b32 s34, -2
	v_mov_b32_e32 v1, v0
	v_mov_b64_e32 v[2:3], v[0:1]
	v_mov_b64_e32 v[4:5], v[0:1]
	v_mov_b64_e32 v[6:7], v[0:1]
	v_mov_b64_e32 v[16:17], v[0:1]
	v_mov_b64_e32 v[18:19], v[0:1]
	v_mov_b64_e32 v[20:21], v[0:1]
	v_mov_b64_e32 v[22:23], v[0:1]
	v_mov_b64_e32 v[32:33], v[0:1]
	v_mov_b64_e32 v[34:35], v[0:1]
	v_mov_b64_e32 v[36:37], v[0:1]
	v_mov_b64_e32 v[38:39], v[0:1]
	v_mov_b64_e32 v[48:49], v[0:1]
	v_mov_b64_e32 v[50:51], v[0:1]
	v_mov_b64_e32 v[52:53], v[0:1]
	v_mov_b64_e32 v[54:55], v[0:1]
	v_mov_b64_e32 v[8:9], v[0:1]
	v_mov_b64_e32 v[10:11], v[0:1]
	v_mov_b64_e32 v[12:13], v[0:1]
	v_mov_b64_e32 v[14:15], v[0:1]
	v_mov_b64_e32 v[24:25], v[0:1]
	v_mov_b64_e32 v[26:27], v[0:1]
	v_mov_b64_e32 v[28:29], v[0:1]
	v_mov_b64_e32 v[30:31], v[0:1]
	v_mov_b64_e32 v[40:41], v[0:1]
	v_mov_b64_e32 v[42:43], v[0:1]
	v_mov_b64_e32 v[44:45], v[0:1]
	v_mov_b64_e32 v[46:47], v[0:1]
	v_mov_b64_e32 v[56:57], v[0:1]
	v_mov_b64_e32 v[58:59], v[0:1]
	v_mov_b64_e32 v[60:61], v[0:1]
	v_mov_b64_e32 v[62:63], v[0:1]
	v_mov_b64_e32 v[64:65], v[0:1]
	v_mov_b64_e32 v[66:67], v[0:1]
	v_mov_b64_e32 v[68:69], v[0:1]
	v_mov_b64_e32 v[70:71], v[0:1]
	v_mov_b64_e32 v[80:81], v[0:1]
	v_mov_b64_e32 v[82:83], v[0:1]
	v_mov_b64_e32 v[84:85], v[0:1]
	v_mov_b64_e32 v[86:87], v[0:1]
	v_mov_b64_e32 v[96:97], v[0:1]
	v_mov_b64_e32 v[98:99], v[0:1]
	v_mov_b64_e32 v[100:101], v[0:1]
	v_mov_b64_e32 v[102:103], v[0:1]
	v_mov_b64_e32 v[112:113], v[0:1]
	v_mov_b64_e32 v[114:115], v[0:1]
	v_mov_b64_e32 v[116:117], v[0:1]
	v_mov_b64_e32 v[118:119], v[0:1]
	v_mov_b64_e32 v[72:73], v[0:1]
	v_mov_b64_e32 v[74:75], v[0:1]
	v_mov_b64_e32 v[76:77], v[0:1]
	v_mov_b64_e32 v[78:79], v[0:1]
	v_mov_b64_e32 v[88:89], v[0:1]
	v_mov_b64_e32 v[90:91], v[0:1]
	v_mov_b64_e32 v[92:93], v[0:1]
	v_mov_b64_e32 v[94:95], v[0:1]
	v_mov_b64_e32 v[104:105], v[0:1]
	v_mov_b64_e32 v[106:107], v[0:1]
	v_mov_b64_e32 v[108:109], v[0:1]
	v_mov_b64_e32 v[110:111], v[0:1]
	v_mov_b64_e32 v[120:121], v[0:1]
	v_mov_b64_e32 v[122:123], v[0:1]
	v_mov_b64_e32 v[124:125], v[0:1]
	v_mov_b64_e32 v[126:127], v[0:1]

.LBB0_1501:
	s_add_i32 s75, s36, 2
	s_add_u32 s34, s30, 0x100
	s_addc_u32 s35, s31, 0
	s_add_i32 s76, 0, 0x10000
	s_cmp_eq_u32 s1, s36
	s_cselect_b32 s41, s25, s35
	s_cselect_b32 s40, s71, s34
	s_cselect_b32 s37, s23, s74
	s_cselect_b32 s36, s72, s73
	s_add_i32 s77, 0, 0x14000
	v_add_u32_e32 v152, s76, v138
	v_add_u32_e32 v168, s77, v138
	ds_read_b128 v[140:143], v152
	ds_read_b128 v[144:147], v152 offset:1024
	ds_read_b128 v[148:151], v152 offset:2048
	ds_read_b128 v[152:155], v152 offset:3072
	ds_read_b128 v[156:159], v168
	ds_read_b128 v[160:163], v168 offset:1024
	ds_read_b128 v[164:167], v168 offset:2048
	ds_read_b128 v[168:171], v168 offset:3072
	v_lshl_add_u64 v[204:205], s[30:31], 0, v[132:133]
	s_add_i32 m0, s58, 0xc000
	ds_read_b128 v[172:175], v139
	ds_read_b128 v[176:179], v139 offset:1024
	ds_read_b128 v[180:183], v139 offset:2048
	ds_read_b128 v[184:187], v139 offset:3072
	ds_read_b128 v[188:191], v139 offset:4096
	ds_read_b128 v[192:195], v139 offset:5120
	ds_read_b128 v[196:199], v139 offset:6144
	ds_read_b128 v[200:203], v139 offset:7168
	global_load_lds_dwordx4 v[204:205], off
	v_lshl_add_u64 v[204:205], s[30:31], 0, v[134:135]
	s_add_i32 m0, s58, 0xe000
	s_nop 0
	global_load_lds_dwordx4 v[204:205], off
	s_waitcnt vmcnt(8)
	s_waitcnt lgkmcnt(0)
	s_barrier
	s_setprio 1
	s_waitcnt lgkmcnt(0)
	v_mfma_f32_16x16x32_bf16 v[124:127], v[140:143], v[172:175], v[124:127]
	v_mfma_f32_16x16x32_bf16 v[108:111], v[148:151], v[172:175], v[108:111]
	v_mfma_f32_16x16x32_bf16 v[120:123], v[140:143], v[180:183], v[120:123]
	v_mfma_f32_16x16x32_bf16 v[104:107], v[148:151], v[180:183], v[104:107]
	v_mfma_f32_16x16x32_bf16 v[116:119], v[140:143], v[188:191], v[116:119]
	v_mfma_f32_16x16x32_bf16 v[100:103], v[148:151], v[188:191], v[100:103]
	v_mfma_f32_16x16x32_bf16 v[112:115], v[140:143], v[196:199], v[112:115]
	v_mfma_f32_16x16x32_bf16 v[96:99], v[148:151], v[196:199], v[96:99]
	v_mfma_f32_16x16x32_bf16 v[124:127], v[144:147], v[176:179], v[124:127]
	v_mfma_f32_16x16x32_bf16 v[108:111], v[152:155], v[176:179], v[108:111]
	v_mfma_f32_16x16x32_bf16 v[120:123], v[144:147], v[184:187], v[120:123]
	v_mfma_f32_16x16x32_bf16 v[104:107], v[152:155], v[184:187], v[104:107]
	v_mfma_f32_16x16x32_bf16 v[116:119], v[144:147], v[192:195], v[116:119]
	v_mfma_f32_16x16x32_bf16 v[100:103], v[152:155], v[192:195], v[100:103]
	v_mfma_f32_16x16x32_bf16 v[112:115], v[144:147], v[200:203], v[112:115]
	v_mfma_f32_16x16x32_bf16 v[96:99], v[152:155], v[200:203], v[96:99]
	s_setprio 0
	s_setprio 1
	v_mfma_f32_16x16x32_bf16 v[92:95], v[156:159], v[172:175], v[92:95]
	v_mfma_f32_16x16x32_bf16 v[76:79], v[164:167], v[172:175], v[76:79]
	v_mfma_f32_16x16x32_bf16 v[88:91], v[156:159], v[180:183], v[88:91]
	v_mfma_f32_16x16x32_bf16 v[72:75], v[164:167], v[180:183], v[72:75]
	v_mfma_f32_16x16x32_bf16 v[84:87], v[156:159], v[188:191], v[84:87]
	v_mfma_f32_16x16x32_bf16 v[68:71], v[164:167], v[188:191], v[68:71]
	v_mfma_f32_16x16x32_bf16 v[80:83], v[156:159], v[196:199], v[80:83]
	v_mfma_f32_16x16x32_bf16 v[64:67], v[164:167], v[196:199], v[64:67]
	v_mfma_f32_16x16x32_bf16 v[92:95], v[160:163], v[176:179], v[92:95]
	v_mfma_f32_16x16x32_bf16 v[76:79], v[168:171], v[176:179], v[76:79]
	v_mfma_f32_16x16x32_bf16 v[88:91], v[160:163], v[184:187], v[88:91]
	v_mfma_f32_16x16x32_bf16 v[72:75], v[168:171], v[184:187], v[72:75]
	v_mfma_f32_16x16x32_bf16 v[84:87], v[160:163], v[192:195], v[84:87]
	v_mfma_f32_16x16x32_bf16 v[68:71], v[168:171], v[192:195], v[68:71]
	v_mfma_f32_16x16x32_bf16 v[80:83], v[160:163], v[200:203], v[80:83]
	v_mfma_f32_16x16x32_bf16 v[64:67], v[168:171], v[200:203], v[64:67]
	s_setprio 0
	s_barrier
	s_add_i32 s30, s76, s56
	v_lshl_add_u64 v[204:205], s[36:37], 0, v[128:129]
	s_mov_b32 m0, s30
	ds_read_b128 v[172:175], v139 offset:16384
	ds_read_b128 v[176:179], v139 offset:17408
	ds_read_b128 v[180:183], v139 offset:18432
	ds_read_b128 v[184:187], v139 offset:19456
	ds_read_b128 v[188:191], v139 offset:20480
	ds_read_b128 v[192:195], v139 offset:21504
	ds_read_b128 v[196:199], v139 offset:22528
	ds_read_b128 v[200:203], v139 offset:23552
	global_load_lds_dwordx4 v[204:205], off
	s_add_i32 m0, s30, 0x2000
	s_add_u32 s30, s36, 0x40000
	v_lshl_add_u64 v[206:207], s[36:37], 0, v[130:131]
	s_addc_u32 s31, s37, 0
	s_add_i32 s76, s77, s56
	global_load_lds_dwordx4 v[206:207], off
	v_lshl_add_u64 v[208:209], s[30:31], 0, v[128:129]
	s_mov_b32 m0, s76
	v_lshl_add_u64 v[210:211], s[40:41], 0, v[130:131]
	global_load_lds_dwordx4 v[208:209], off
	v_lshl_add_u64 v[208:209], s[30:31], 0, v[130:131]
	s_add_i32 m0, s76, 0x2000
	s_nop 0
	global_load_lds_dwordx4 v[208:209], off
	v_lshl_add_u64 v[208:209], s[40:41], 0, v[128:129]
	s_mov_b32 m0, s58
	s_nop 0
	global_load_lds_dwordx4 v[208:209], off
	s_mov_b32 m0, s60
	s_nop 0
	global_load_lds_dwordx4 v[210:211], off
	s_waitcnt vmcnt(8)
	s_waitcnt lgkmcnt(0)
	s_barrier
	s_setprio 1
	s_waitcnt lgkmcnt(0)
	v_mfma_f32_16x16x32_bf16 v[60:63], v[140:143], v[172:175], v[60:63]
	v_mfma_f32_16x16x32_bf16 v[44:47], v[148:151], v[172:175], v[44:47]
	v_mfma_f32_16x16x32_bf16 v[56:59], v[140:143], v[180:183], v[56:59]
	v_mfma_f32_16x16x32_bf16 v[40:43], v[148:151], v[180:183], v[40:43]
	v_mfma_f32_16x16x32_bf16 v[52:55], v[140:143], v[188:191], v[52:55]
	v_mfma_f32_16x16x32_bf16 v[36:39], v[148:151], v[188:191], v[36:39]
	v_mfma_f32_16x16x32_bf16 v[48:51], v[140:143], v[196:199], v[48:51]
	v_mfma_f32_16x16x32_bf16 v[32:35], v[148:151], v[196:199], v[32:35]
	v_mfma_f32_16x16x32_bf16 v[60:63], v[144:147], v[176:179], v[60:63]
	v_mfma_f32_16x16x32_bf16 v[44:47], v[152:155], v[176:179], v[44:47]
	v_mfma_f32_16x16x32_bf16 v[56:59], v[144:147], v[184:187], v[56:59]
	v_mfma_f32_16x16x32_bf16 v[40:43], v[152:155], v[184:187], v[40:43]
	v_mfma_f32_16x16x32_bf16 v[52:55], v[144:147], v[192:195], v[52:55]
	v_mfma_f32_16x16x32_bf16 v[36:39], v[152:155], v[192:195], v[36:39]
	v_mfma_f32_16x16x32_bf16 v[48:51], v[144:147], v[200:203], v[48:51]
	v_mfma_f32_16x16x32_bf16 v[32:35], v[152:155], v[200:203], v[32:35]
	s_setprio 0
	s_setprio 1
	v_mfma_f32_16x16x32_bf16 v[28:31], v[156:159], v[172:175], v[28:31]
	v_mfma_f32_16x16x32_bf16 v[12:15], v[164:167], v[172:175], v[12:15]
	v_mfma_f32_16x16x32_bf16 v[24:27], v[156:159], v[180:183], v[24:27]
	v_mfma_f32_16x16x32_bf16 v[8:11], v[164:167], v[180:183], v[8:11]
	v_mfma_f32_16x16x32_bf16 v[20:23], v[156:159], v[188:191], v[20:23]
	v_mfma_f32_16x16x32_bf16 v[4:7], v[164:167], v[188:191], v[4:7]
	v_mfma_f32_16x16x32_bf16 v[16:19], v[156:159], v[196:199], v[16:19]
	v_mfma_f32_16x16x32_bf16 v[0:3], v[164:167], v[196:199], v[0:3]
	v_mfma_f32_16x16x32_bf16 v[28:31], v[160:163], v[176:179], v[28:31]
	v_mfma_f32_16x16x32_bf16 v[12:15], v[168:171], v[176:179], v[12:15]
	v_mfma_f32_16x16x32_bf16 v[24:27], v[160:163], v[184:187], v[24:27]
	v_mfma_f32_16x16x32_bf16 v[8:11], v[168:171], v[184:187], v[8:11]
	v_mfma_f32_16x16x32_bf16 v[20:23], v[160:163], v[192:195], v[20:23]
	v_mfma_f32_16x16x32_bf16 v[4:7], v[168:171], v[192:195], v[4:7]
	v_mfma_f32_16x16x32_bf16 v[16:19], v[160:163], v[200:203], v[16:19]
	v_mfma_f32_16x16x32_bf16 v[0:3], v[168:171], v[200:203], v[0:3]
	s_setprio 0
	s_barrier
	s_add_i32 s76, 0, 0x18000
	s_add_i32 s77, 0, 0x1c000
	v_add_u32_e32 v152, s76, v138
	v_add_u32_e32 v168, s77, v138
	ds_read_b128 v[140:143], v152
	ds_read_b128 v[144:147], v152 offset:1024
	ds_read_b128 v[148:151], v152 offset:2048
	ds_read_b128 v[152:155], v152 offset:3072
	ds_read_b128 v[156:159], v168
	ds_read_b128 v[160:163], v168 offset:1024
	ds_read_b128 v[164:167], v168 offset:2048
	ds_read_b128 v[168:171], v168 offset:3072
	s_add_u32 s30, s40, 0x40000
	s_addc_u32 s31, s41, 0
	s_mov_b32 m0, s61
	v_lshl_add_u64 v[212:213], s[30:31], 0, v[128:129]
	ds_read_b128 v[172:175], v139 offset:32768
	ds_read_b128 v[176:179], v139 offset:33792
	ds_read_b128 v[180:183], v139 offset:34816
	ds_read_b128 v[184:187], v139 offset:35840
	ds_read_b128 v[188:191], v139 offset:36864
	ds_read_b128 v[192:195], v139 offset:37888
	ds_read_b128 v[196:199], v139 offset:38912
	ds_read_b128 v[200:203], v139 offset:39936
	global_load_lds_dwordx4 v[212:213], off
	v_lshl_add_u64 v[212:213], s[30:31], 0, v[130:131]
	s_mov_b32 m0, s62
	s_nop 0
	global_load_lds_dwordx4 v[212:213], off
	s_waitcnt vmcnt(8)
	s_waitcnt lgkmcnt(0)
	s_barrier
	s_setprio 1
	s_waitcnt lgkmcnt(0)
	v_mfma_f32_16x16x32_bf16 v[124:127], v[140:143], v[172:175], v[124:127]
	v_mfma_f32_16x16x32_bf16 v[108:111], v[148:151], v[172:175], v[108:111]
	v_mfma_f32_16x16x32_bf16 v[120:123], v[140:143], v[180:183], v[120:123]
	v_mfma_f32_16x16x32_bf16 v[104:107], v[148:151], v[180:183], v[104:107]
	v_mfma_f32_16x16x32_bf16 v[116:119], v[140:143], v[188:191], v[116:119]
	v_mfma_f32_16x16x32_bf16 v[100:103], v[148:151], v[188:191], v[100:103]
	v_mfma_f32_16x16x32_bf16 v[112:115], v[140:143], v[196:199], v[112:115]
	v_mfma_f32_16x16x32_bf16 v[96:99], v[148:151], v[196:199], v[96:99]
	v_mfma_f32_16x16x32_bf16 v[124:127], v[144:147], v[176:179], v[124:127]
	v_mfma_f32_16x16x32_bf16 v[108:111], v[152:155], v[176:179], v[108:111]
	v_mfma_f32_16x16x32_bf16 v[120:123], v[144:147], v[184:187], v[120:123]
	v_mfma_f32_16x16x32_bf16 v[104:107], v[152:155], v[184:187], v[104:107]
	v_mfma_f32_16x16x32_bf16 v[116:119], v[144:147], v[192:195], v[116:119]
	v_mfma_f32_16x16x32_bf16 v[100:103], v[152:155], v[192:195], v[100:103]
	v_mfma_f32_16x16x32_bf16 v[112:115], v[144:147], v[200:203], v[112:115]
	v_mfma_f32_16x16x32_bf16 v[96:99], v[152:155], v[200:203], v[96:99]
	s_setprio 0
	s_setprio 1
	v_mfma_f32_16x16x32_bf16 v[92:95], v[156:159], v[172:175], v[92:95]
	v_mfma_f32_16x16x32_bf16 v[76:79], v[164:167], v[172:175], v[76:79]
	v_mfma_f32_16x16x32_bf16 v[88:91], v[156:159], v[180:183], v[88:91]
	v_mfma_f32_16x16x32_bf16 v[72:75], v[164:167], v[180:183], v[72:75]
	v_mfma_f32_16x16x32_bf16 v[84:87], v[156:159], v[188:191], v[84:87]
	v_mfma_f32_16x16x32_bf16 v[68:71], v[164:167], v[188:191], v[68:71]
	v_mfma_f32_16x16x32_bf16 v[80:83], v[156:159], v[196:199], v[80:83]
	v_mfma_f32_16x16x32_bf16 v[64:67], v[164:167], v[196:199], v[64:67]
	v_mfma_f32_16x16x32_bf16 v[92:95], v[160:163], v[176:179], v[92:95]
	v_mfma_f32_16x16x32_bf16 v[76:79], v[168:171], v[176:179], v[76:79]
	v_mfma_f32_16x16x32_bf16 v[88:91], v[160:163], v[184:187], v[88:91]
	v_mfma_f32_16x16x32_bf16 v[72:75], v[168:171], v[184:187], v[72:75]
	v_mfma_f32_16x16x32_bf16 v[84:87], v[160:163], v[192:195], v[84:87]
	v_mfma_f32_16x16x32_bf16 v[68:71], v[168:171], v[192:195], v[68:71]
	v_mfma_f32_16x16x32_bf16 v[80:83], v[160:163], v[200:203], v[80:83]
	v_mfma_f32_16x16x32_bf16 v[64:67], v[168:171], v[200:203], v[64:67]
	s_setprio 0
	s_barrier
	s_add_i32 s30, s76, s56
	v_lshl_add_u64 v[204:205], v[204:205], 0, s[6:7]
	s_mov_b32 m0, s30
	ds_read_b128 v[172:175], v139 offset:49152
	ds_read_b128 v[176:179], v139 offset:50176
	ds_read_b128 v[180:183], v139 offset:51200
	ds_read_b128 v[184:187], v139 offset:52224
	ds_read_b128 v[188:191], v139 offset:53248
	ds_read_b128 v[192:195], v139 offset:54272
	ds_read_b128 v[196:199], v139 offset:55296
	ds_read_b128 v[200:203], v139 offset:56320
	global_load_lds_dwordx4 v[204:205], off
	s_add_i32 m0, s30, 0x2000
	s_add_u32 s30, s36, 0x40080
	v_lshl_add_u64 v[204:205], v[206:207], 0, s[6:7]
	s_addc_u32 s31, s37, 0
	s_add_i32 s36, s77, s56
	global_load_lds_dwordx4 v[204:205], off
	v_lshl_add_u64 v[204:205], s[30:31], 0, v[128:129]
	s_mov_b32 m0, s36
	s_nop 0
	global_load_lds_dwordx4 v[204:205], off
	v_lshl_add_u64 v[204:205], s[30:31], 0, v[130:131]
	s_add_i32 m0, s36, 0x2000
	s_nop 0
	global_load_lds_dwordx4 v[204:205], off
	v_lshl_add_u64 v[204:205], v[208:209], 0, s[6:7]
	s_mov_b32 m0, s63
	s_nop 0
	global_load_lds_dwordx4 v[204:205], off
	v_lshl_add_u64 v[204:205], v[210:211], 0, s[6:7]
	s_mov_b32 m0, s64
	s_nop 0
	global_load_lds_dwordx4 v[204:205], off
	s_waitcnt vmcnt(8)
	s_waitcnt lgkmcnt(0)
	s_barrier
	s_setprio 1
	s_waitcnt lgkmcnt(0)
	v_mfma_f32_16x16x32_bf16 v[60:63], v[140:143], v[172:175], v[60:63]
	v_mfma_f32_16x16x32_bf16 v[44:47], v[148:151], v[172:175], v[44:47]
	v_mfma_f32_16x16x32_bf16 v[56:59], v[140:143], v[180:183], v[56:59]
	v_mfma_f32_16x16x32_bf16 v[40:43], v[148:151], v[180:183], v[40:43]
	v_mfma_f32_16x16x32_bf16 v[52:55], v[140:143], v[188:191], v[52:55]
	v_mfma_f32_16x16x32_bf16 v[36:39], v[148:151], v[188:191], v[36:39]
	v_mfma_f32_16x16x32_bf16 v[48:51], v[140:143], v[196:199], v[48:51]
	v_mfma_f32_16x16x32_bf16 v[32:35], v[148:151], v[196:199], v[32:35]
	v_mfma_f32_16x16x32_bf16 v[60:63], v[144:147], v[176:179], v[60:63]
	v_mfma_f32_16x16x32_bf16 v[44:47], v[152:155], v[176:179], v[44:47]
	v_mfma_f32_16x16x32_bf16 v[56:59], v[144:147], v[184:187], v[56:59]
	v_mfma_f32_16x16x32_bf16 v[40:43], v[152:155], v[184:187], v[40:43]
	v_mfma_f32_16x16x32_bf16 v[52:55], v[144:147], v[192:195], v[52:55]
	v_mfma_f32_16x16x32_bf16 v[36:39], v[152:155], v[192:195], v[36:39]
	v_mfma_f32_16x16x32_bf16 v[48:51], v[144:147], v[200:203], v[48:51]
	v_mfma_f32_16x16x32_bf16 v[32:35], v[152:155], v[200:203], v[32:35]
	s_setprio 0
	s_setprio 1
	v_mfma_f32_16x16x32_bf16 v[28:31], v[156:159], v[172:175], v[28:31]
	v_mfma_f32_16x16x32_bf16 v[12:15], v[164:167], v[172:175], v[12:15]
	v_mfma_f32_16x16x32_bf16 v[24:27], v[156:159], v[180:183], v[24:27]
	v_mfma_f32_16x16x32_bf16 v[8:11], v[164:167], v[180:183], v[8:11]
	v_mfma_f32_16x16x32_bf16 v[20:23], v[156:159], v[188:191], v[20:23]
	v_mfma_f32_16x16x32_bf16 v[4:7], v[164:167], v[188:191], v[4:7]
	v_mfma_f32_16x16x32_bf16 v[16:19], v[156:159], v[196:199], v[16:19]
	v_mfma_f32_16x16x32_bf16 v[0:3], v[164:167], v[196:199], v[0:3]
	v_mfma_f32_16x16x32_bf16 v[28:31], v[160:163], v[176:179], v[28:31]
	v_mfma_f32_16x16x32_bf16 v[12:15], v[168:171], v[176:179], v[12:15]
	v_mfma_f32_16x16x32_bf16 v[24:27], v[160:163], v[184:187], v[24:27]
	v_mfma_f32_16x16x32_bf16 v[8:11], v[168:171], v[184:187], v[8:11]
	v_mfma_f32_16x16x32_bf16 v[20:23], v[160:163], v[192:195], v[20:23]
	v_mfma_f32_16x16x32_bf16 v[4:7], v[168:171], v[192:195], v[4:7]
	v_mfma_f32_16x16x32_bf16 v[16:19], v[160:163], v[200:203], v[16:19]
	v_mfma_f32_16x16x32_bf16 v[0:3], v[168:171], v[200:203], v[0:3]
	s_setprio 0
	s_barrier
	s_add_u32 s73, s73, 0x100
	s_addc_u32 s74, s74, 0
	s_cmp_ge_u32 s75, s92
	s_mov_b64 s[30:31], s[34:35]
	s_mov_b32 s36, s75
	s_cbranch_scc0 .LBB0_1501
	s_andn2_b64 vcc, exec, s[50:51]
	s_cbranch_vccnz .LBB0_1493
	v_mov_b32_e32 v0, 0
	s_mov_b32 s66, s22
	s_mov_b32 s65, s24
	s_mov_b64 s[18:19], s[28:29]
	s_mov_b64 s[20:21], s[26:27]
	s_mov_b32 s68, s70
	v_mov_b32_e32 v1, v0
	v_mov_b64_e32 v[2:3], v[0:1]
	v_mov_b64_e32 v[16:17], v[0:1]
	v_mov_b64_e32 v[18:19], v[0:1]
	v_mov_b64_e32 v[4:5], v[0:1]
	v_mov_b64_e32 v[6:7], v[0:1]
	v_mov_b64_e32 v[20:21], v[0:1]
	v_mov_b64_e32 v[22:23], v[0:1]
	v_mov_b64_e32 v[8:9], v[0:1]
	v_mov_b64_e32 v[10:11], v[0:1]
	v_mov_b64_e32 v[24:25], v[0:1]
	v_mov_b64_e32 v[26:27], v[0:1]
	v_mov_b64_e32 v[12:13], v[0:1]
	v_mov_b64_e32 v[14:15], v[0:1]
	v_mov_b64_e32 v[28:29], v[0:1]
	v_mov_b64_e32 v[30:31], v[0:1]
	v_mov_b64_e32 v[32:33], v[0:1]
	v_mov_b64_e32 v[34:35], v[0:1]
	v_mov_b64_e32 v[48:49], v[0:1]
	v_mov_b64_e32 v[50:51], v[0:1]
	v_mov_b64_e32 v[36:37], v[0:1]
	v_mov_b64_e32 v[38:39], v[0:1]
	v_mov_b64_e32 v[52:53], v[0:1]
	v_mov_b64_e32 v[54:55], v[0:1]
	v_mov_b64_e32 v[40:41], v[0:1]
	v_mov_b64_e32 v[42:43], v[0:1]
	v_mov_b64_e32 v[56:57], v[0:1]
	v_mov_b64_e32 v[58:59], v[0:1]
	v_mov_b64_e32 v[44:45], v[0:1]
	v_mov_b64_e32 v[46:47], v[0:1]
	v_mov_b64_e32 v[60:61], v[0:1]
	v_mov_b64_e32 v[62:63], v[0:1]
	v_mov_b64_e32 v[64:65], v[0:1]
	v_mov_b64_e32 v[66:67], v[0:1]
	v_mov_b64_e32 v[80:81], v[0:1]
	v_mov_b64_e32 v[82:83], v[0:1]
	v_mov_b64_e32 v[68:69], v[0:1]
	v_mov_b64_e32 v[70:71], v[0:1]
	v_mov_b64_e32 v[84:85], v[0:1]
	v_mov_b64_e32 v[86:87], v[0:1]
	v_mov_b64_e32 v[72:73], v[0:1]
	v_mov_b64_e32 v[74:75], v[0:1]
	v_mov_b64_e32 v[88:89], v[0:1]
	v_mov_b64_e32 v[90:91], v[0:1]
	v_mov_b64_e32 v[76:77], v[0:1]
	v_mov_b64_e32 v[78:79], v[0:1]
	v_mov_b64_e32 v[92:93], v[0:1]
	v_mov_b64_e32 v[94:95], v[0:1]
	v_mov_b64_e32 v[96:97], v[0:1]
	v_mov_b64_e32 v[98:99], v[0:1]
	v_mov_b64_e32 v[112:113], v[0:1]
	v_mov_b64_e32 v[114:115], v[0:1]
	v_mov_b64_e32 v[100:101], v[0:1]
	v_mov_b64_e32 v[102:103], v[0:1]
	v_mov_b64_e32 v[116:117], v[0:1]
	v_mov_b64_e32 v[118:119], v[0:1]
	v_mov_b64_e32 v[104:105], v[0:1]
	v_mov_b64_e32 v[106:107], v[0:1]
	v_mov_b64_e32 v[120:121], v[0:1]
	v_mov_b64_e32 v[122:123], v[0:1]
	v_mov_b64_e32 v[108:109], v[0:1]
	v_mov_b64_e32 v[110:111], v[0:1]
	v_mov_b64_e32 v[124:125], v[0:1]
	v_mov_b64_e32 v[126:127], v[0:1]
	s_branch .LBB0_1493

.LBB0_1765:
	s_ashr_i32 s25, s24, 31
	s_lshl_b64 s[26:27], s[24:25], 19
	s_add_u32 s26, s5, s26
	s_addc_u32 s27, s38, s27
	s_and_b64 s[28:29], s[48:49], exec
	s_cselect_b32 s25, s27, s31
	s_cselect_b32 s62, s26, s30
	s_ashr_i32 s23, s22, 31
	s_lshl_b64 s[28:29], s[22:23], 19
	s_add_u32 s28, s39, s28
	s_addc_u32 s29, s40, s29
	s_and_b64 s[36:37], s[48:49], exec
	s_cselect_b32 s23, s29, s35
	s_cselect_b32 s63, s28, s34
	s_add_u32 s30, s30, 0x40080
	s_addc_u32 s31, s31, 0
	s_add_u32 s64, s34, 0x100
	v_mov_b32_e32 v0, 0
	s_addc_u32 s65, s35, 0
	s_mov_b32 s66, -2
	v_mov_b32_e32 v1, v0
	v_mov_b64_e32 v[2:3], v[0:1]
	v_mov_b64_e32 v[4:5], v[0:1]
	v_mov_b64_e32 v[6:7], v[0:1]
	v_mov_b64_e32 v[16:17], v[0:1]
	v_mov_b64_e32 v[18:19], v[0:1]
	v_mov_b64_e32 v[20:21], v[0:1]
	v_mov_b64_e32 v[22:23], v[0:1]
	v_mov_b64_e32 v[32:33], v[0:1]
	v_mov_b64_e32 v[34:35], v[0:1]
	v_mov_b64_e32 v[36:37], v[0:1]
	v_mov_b64_e32 v[38:39], v[0:1]
	v_mov_b64_e32 v[48:49], v[0:1]
	v_mov_b64_e32 v[50:51], v[0:1]
	v_mov_b64_e32 v[52:53], v[0:1]
	v_mov_b64_e32 v[54:55], v[0:1]
	v_mov_b64_e32 v[8:9], v[0:1]
	v_mov_b64_e32 v[10:11], v[0:1]
	v_mov_b64_e32 v[12:13], v[0:1]
	v_mov_b64_e32 v[14:15], v[0:1]
	v_mov_b64_e32 v[24:25], v[0:1]
	v_mov_b64_e32 v[26:27], v[0:1]
	v_mov_b64_e32 v[28:29], v[0:1]
	v_mov_b64_e32 v[30:31], v[0:1]
	v_mov_b64_e32 v[40:41], v[0:1]
	v_mov_b64_e32 v[42:43], v[0:1]
	v_mov_b64_e32 v[44:45], v[0:1]
	v_mov_b64_e32 v[46:47], v[0:1]
	v_mov_b64_e32 v[56:57], v[0:1]
	v_mov_b64_e32 v[58:59], v[0:1]
	v_mov_b64_e32 v[60:61], v[0:1]
	v_mov_b64_e32 v[62:63], v[0:1]
	v_mov_b64_e32 v[64:65], v[0:1]
	v_mov_b64_e32 v[66:67], v[0:1]
	v_mov_b64_e32 v[68:69], v[0:1]
	v_mov_b64_e32 v[70:71], v[0:1]
	v_mov_b64_e32 v[80:81], v[0:1]
	v_mov_b64_e32 v[82:83], v[0:1]
	v_mov_b64_e32 v[84:85], v[0:1]
	v_mov_b64_e32 v[86:87], v[0:1]
	v_mov_b64_e32 v[96:97], v[0:1]
	v_mov_b64_e32 v[98:99], v[0:1]
	v_mov_b64_e32 v[100:101], v[0:1]
	v_mov_b64_e32 v[102:103], v[0:1]
	v_mov_b64_e32 v[112:113], v[0:1]
	v_mov_b64_e32 v[114:115], v[0:1]
	v_mov_b64_e32 v[116:117], v[0:1]
	v_mov_b64_e32 v[118:119], v[0:1]
	v_mov_b64_e32 v[72:73], v[0:1]
	v_mov_b64_e32 v[74:75], v[0:1]
	v_mov_b64_e32 v[76:77], v[0:1]
	v_mov_b64_e32 v[78:79], v[0:1]
	v_mov_b64_e32 v[88:89], v[0:1]
	v_mov_b64_e32 v[90:91], v[0:1]
	v_mov_b64_e32 v[92:93], v[0:1]
	v_mov_b64_e32 v[94:95], v[0:1]
	v_mov_b64_e32 v[104:105], v[0:1]
	v_mov_b64_e32 v[106:107], v[0:1]
	v_mov_b64_e32 v[108:109], v[0:1]
	v_mov_b64_e32 v[110:111], v[0:1]
	v_mov_b64_e32 v[120:121], v[0:1]
	v_mov_b64_e32 v[122:123], v[0:1]
	v_mov_b64_e32 v[124:125], v[0:1]
	v_mov_b64_e32 v[126:127], v[0:1]

.LBB0_1859:
	s_add_i32 s73, s36, 2
	s_add_u32 s34, s30, 0x100
	s_addc_u32 s35, s31, 0
	s_add_i32 s74, 0, 0x10000
	s_cmp_eq_u32 s0, s36
	s_cselect_b32 s41, s25, s35
	s_cselect_b32 s40, s68, s34
	s_cselect_b32 s37, s23, s72
	s_cselect_b32 s36, s70, s71
	s_add_i32 s75, 0, 0x14000
	v_add_u32_e32 v152, s74, v138
	v_add_u32_e32 v168, s75, v138
	ds_read_b128 v[140:143], v152
	ds_read_b128 v[144:147], v152 offset:1024
	ds_read_b128 v[148:151], v152 offset:2048
	ds_read_b128 v[152:155], v152 offset:3072
	ds_read_b128 v[156:159], v168
	ds_read_b128 v[160:163], v168 offset:1024
	ds_read_b128 v[164:167], v168 offset:2048
	ds_read_b128 v[168:171], v168 offset:3072
	v_lshl_add_u64 v[204:205], s[30:31], 0, v[132:133]
	s_add_i32 m0, s56, 0xc000
	ds_read_b128 v[172:175], v139
	ds_read_b128 v[176:179], v139 offset:1024
	ds_read_b128 v[180:183], v139 offset:2048
	ds_read_b128 v[184:187], v139 offset:3072
	ds_read_b128 v[188:191], v139 offset:4096
	ds_read_b128 v[192:195], v139 offset:5120
	ds_read_b128 v[196:199], v139 offset:6144
	ds_read_b128 v[200:203], v139 offset:7168
	global_load_lds_dwordx4 v[204:205], off
	v_lshl_add_u64 v[204:205], s[30:31], 0, v[134:135]
	s_add_i32 m0, s56, 0xe000
	s_nop 0
	global_load_lds_dwordx4 v[204:205], off
	s_waitcnt vmcnt(8)
	s_waitcnt lgkmcnt(0)
	s_barrier
	s_setprio 1
	s_waitcnt lgkmcnt(0)
	v_mfma_f32_16x16x32_bf16 v[124:127], v[140:143], v[172:175], v[124:127]
	v_mfma_f32_16x16x32_bf16 v[108:111], v[148:151], v[172:175], v[108:111]
	v_mfma_f32_16x16x32_bf16 v[120:123], v[140:143], v[180:183], v[120:123]
	v_mfma_f32_16x16x32_bf16 v[104:107], v[148:151], v[180:183], v[104:107]
	v_mfma_f32_16x16x32_bf16 v[116:119], v[140:143], v[188:191], v[116:119]
	v_mfma_f32_16x16x32_bf16 v[100:103], v[148:151], v[188:191], v[100:103]
	v_mfma_f32_16x16x32_bf16 v[112:115], v[140:143], v[196:199], v[112:115]
	v_mfma_f32_16x16x32_bf16 v[96:99], v[148:151], v[196:199], v[96:99]
	v_mfma_f32_16x16x32_bf16 v[124:127], v[144:147], v[176:179], v[124:127]
	v_mfma_f32_16x16x32_bf16 v[108:111], v[152:155], v[176:179], v[108:111]
	v_mfma_f32_16x16x32_bf16 v[120:123], v[144:147], v[184:187], v[120:123]
	v_mfma_f32_16x16x32_bf16 v[104:107], v[152:155], v[184:187], v[104:107]
	v_mfma_f32_16x16x32_bf16 v[116:119], v[144:147], v[192:195], v[116:119]
	v_mfma_f32_16x16x32_bf16 v[100:103], v[152:155], v[192:195], v[100:103]
	v_mfma_f32_16x16x32_bf16 v[112:115], v[144:147], v[200:203], v[112:115]
	v_mfma_f32_16x16x32_bf16 v[96:99], v[152:155], v[200:203], v[96:99]
	s_setprio 0
	s_setprio 1
	v_mfma_f32_16x16x32_bf16 v[92:95], v[156:159], v[172:175], v[92:95]
	v_mfma_f32_16x16x32_bf16 v[76:79], v[164:167], v[172:175], v[76:79]
	v_mfma_f32_16x16x32_bf16 v[88:91], v[156:159], v[180:183], v[88:91]
	v_mfma_f32_16x16x32_bf16 v[72:75], v[164:167], v[180:183], v[72:75]
	v_mfma_f32_16x16x32_bf16 v[84:87], v[156:159], v[188:191], v[84:87]
	v_mfma_f32_16x16x32_bf16 v[68:71], v[164:167], v[188:191], v[68:71]
	v_mfma_f32_16x16x32_bf16 v[80:83], v[156:159], v[196:199], v[80:83]
	v_mfma_f32_16x16x32_bf16 v[64:67], v[164:167], v[196:199], v[64:67]
	v_mfma_f32_16x16x32_bf16 v[92:95], v[160:163], v[176:179], v[92:95]
	v_mfma_f32_16x16x32_bf16 v[76:79], v[168:171], v[176:179], v[76:79]
	v_mfma_f32_16x16x32_bf16 v[88:91], v[160:163], v[184:187], v[88:91]
	v_mfma_f32_16x16x32_bf16 v[72:75], v[168:171], v[184:187], v[72:75]
	v_mfma_f32_16x16x32_bf16 v[84:87], v[160:163], v[192:195], v[84:87]
	v_mfma_f32_16x16x32_bf16 v[68:71], v[168:171], v[192:195], v[68:71]
	v_mfma_f32_16x16x32_bf16 v[80:83], v[160:163], v[200:203], v[80:83]
	v_mfma_f32_16x16x32_bf16 v[64:67], v[168:171], v[200:203], v[64:67]
	s_setprio 0
	s_barrier
	s_add_i32 s30, s74, s54
	v_lshl_add_u64 v[204:205], s[36:37], 0, v[128:129]
	s_mov_b32 m0, s30
	ds_read_b128 v[172:175], v139 offset:16384
	ds_read_b128 v[176:179], v139 offset:17408
	ds_read_b128 v[180:183], v139 offset:18432
	ds_read_b128 v[184:187], v139 offset:19456
	ds_read_b128 v[188:191], v139 offset:20480
	ds_read_b128 v[192:195], v139 offset:21504
	ds_read_b128 v[196:199], v139 offset:22528
	ds_read_b128 v[200:203], v139 offset:23552
	global_load_lds_dwordx4 v[204:205], off
	s_add_i32 m0, s30, 0x2000
	s_add_u32 s30, s36, 0x100000
	v_lshl_add_u64 v[206:207], s[36:37], 0, v[130:131]
	s_addc_u32 s31, s37, 0
	s_add_i32 s74, s75, s54
	global_load_lds_dwordx4 v[206:207], off
	v_lshl_add_u64 v[208:209], s[30:31], 0, v[128:129]
	s_mov_b32 m0, s74
	v_lshl_add_u64 v[210:211], s[40:41], 0, v[130:131]
	global_load_lds_dwordx4 v[208:209], off
	v_lshl_add_u64 v[208:209], s[30:31], 0, v[130:131]
	s_add_i32 m0, s74, 0x2000
	s_nop 0
	global_load_lds_dwordx4 v[208:209], off
	v_lshl_add_u64 v[208:209], s[40:41], 0, v[128:129]
	s_mov_b32 m0, s56
	s_nop 0
	global_load_lds_dwordx4 v[208:209], off
	s_mov_b32 m0, s58
	s_nop 0
	global_load_lds_dwordx4 v[210:211], off
	s_waitcnt vmcnt(8)
	s_waitcnt lgkmcnt(0)
	s_barrier
	s_setprio 1
	s_waitcnt lgkmcnt(0)
	v_mfma_f32_16x16x32_bf16 v[60:63], v[140:143], v[172:175], v[60:63]
	v_mfma_f32_16x16x32_bf16 v[44:47], v[148:151], v[172:175], v[44:47]
	v_mfma_f32_16x16x32_bf16 v[56:59], v[140:143], v[180:183], v[56:59]
	v_mfma_f32_16x16x32_bf16 v[40:43], v[148:151], v[180:183], v[40:43]
	v_mfma_f32_16x16x32_bf16 v[52:55], v[140:143], v[188:191], v[52:55]
	v_mfma_f32_16x16x32_bf16 v[36:39], v[148:151], v[188:191], v[36:39]
	v_mfma_f32_16x16x32_bf16 v[48:51], v[140:143], v[196:199], v[48:51]
	v_mfma_f32_16x16x32_bf16 v[32:35], v[148:151], v[196:199], v[32:35]
	v_mfma_f32_16x16x32_bf16 v[60:63], v[144:147], v[176:179], v[60:63]
	v_mfma_f32_16x16x32_bf16 v[44:47], v[152:155], v[176:179], v[44:47]
	v_mfma_f32_16x16x32_bf16 v[56:59], v[144:147], v[184:187], v[56:59]
	v_mfma_f32_16x16x32_bf16 v[40:43], v[152:155], v[184:187], v[40:43]
	v_mfma_f32_16x16x32_bf16 v[52:55], v[144:147], v[192:195], v[52:55]
	v_mfma_f32_16x16x32_bf16 v[36:39], v[152:155], v[192:195], v[36:39]
	v_mfma_f32_16x16x32_bf16 v[48:51], v[144:147], v[200:203], v[48:51]
	v_mfma_f32_16x16x32_bf16 v[32:35], v[152:155], v[200:203], v[32:35]
	s_setprio 0
	s_setprio 1
	v_mfma_f32_16x16x32_bf16 v[28:31], v[156:159], v[172:175], v[28:31]
	v_mfma_f32_16x16x32_bf16 v[12:15], v[164:167], v[172:175], v[12:15]
	v_mfma_f32_16x16x32_bf16 v[24:27], v[156:159], v[180:183], v[24:27]
	v_mfma_f32_16x16x32_bf16 v[8:11], v[164:167], v[180:183], v[8:11]
	v_mfma_f32_16x16x32_bf16 v[20:23], v[156:159], v[188:191], v[20:23]
	v_mfma_f32_16x16x32_bf16 v[4:7], v[164:167], v[188:191], v[4:7]
	v_mfma_f32_16x16x32_bf16 v[16:19], v[156:159], v[196:199], v[16:19]
	v_mfma_f32_16x16x32_bf16 v[0:3], v[164:167], v[196:199], v[0:3]
	v_mfma_f32_16x16x32_bf16 v[28:31], v[160:163], v[176:179], v[28:31]
	v_mfma_f32_16x16x32_bf16 v[12:15], v[168:171], v[176:179], v[12:15]
	v_mfma_f32_16x16x32_bf16 v[24:27], v[160:163], v[184:187], v[24:27]
	v_mfma_f32_16x16x32_bf16 v[8:11], v[168:171], v[184:187], v[8:11]
	v_mfma_f32_16x16x32_bf16 v[20:23], v[160:163], v[192:195], v[20:23]
	v_mfma_f32_16x16x32_bf16 v[4:7], v[168:171], v[192:195], v[4:7]
	v_mfma_f32_16x16x32_bf16 v[16:19], v[160:163], v[200:203], v[16:19]
	v_mfma_f32_16x16x32_bf16 v[0:3], v[168:171], v[200:203], v[0:3]
	s_setprio 0
	s_barrier
	s_add_i32 s74, 0, 0x18000
	s_add_i32 s75, 0, 0x1c000
	v_add_u32_e32 v152, s74, v138
	v_add_u32_e32 v168, s75, v138
	ds_read_b128 v[140:143], v152
	ds_read_b128 v[144:147], v152 offset:1024
	ds_read_b128 v[148:151], v152 offset:2048
	ds_read_b128 v[152:155], v152 offset:3072
	ds_read_b128 v[156:159], v168
	ds_read_b128 v[160:163], v168 offset:1024
	ds_read_b128 v[164:167], v168 offset:2048
	ds_read_b128 v[168:171], v168 offset:3072
	s_add_u32 s30, s40, 0x100000
	s_addc_u32 s31, s41, 0
	s_mov_b32 m0, s59
	v_lshl_add_u64 v[212:213], s[30:31], 0, v[128:129]
	ds_read_b128 v[172:175], v139 offset:32768
	ds_read_b128 v[176:179], v139 offset:33792
	ds_read_b128 v[180:183], v139 offset:34816
	ds_read_b128 v[184:187], v139 offset:35840
	ds_read_b128 v[188:191], v139 offset:36864
	ds_read_b128 v[192:195], v139 offset:37888
	ds_read_b128 v[196:199], v139 offset:38912
	ds_read_b128 v[200:203], v139 offset:39936
	global_load_lds_dwordx4 v[212:213], off
	v_lshl_add_u64 v[212:213], s[30:31], 0, v[130:131]
	s_mov_b32 m0, s60
	s_nop 0
	global_load_lds_dwordx4 v[212:213], off
	s_waitcnt vmcnt(8)
	s_waitcnt lgkmcnt(0)
	s_barrier
	s_setprio 1
	s_waitcnt lgkmcnt(0)
	v_mfma_f32_16x16x32_bf16 v[124:127], v[140:143], v[172:175], v[124:127]
	v_mfma_f32_16x16x32_bf16 v[108:111], v[148:151], v[172:175], v[108:111]
	v_mfma_f32_16x16x32_bf16 v[120:123], v[140:143], v[180:183], v[120:123]
	v_mfma_f32_16x16x32_bf16 v[104:107], v[148:151], v[180:183], v[104:107]
	v_mfma_f32_16x16x32_bf16 v[116:119], v[140:143], v[188:191], v[116:119]
	v_mfma_f32_16x16x32_bf16 v[100:103], v[148:151], v[188:191], v[100:103]
	v_mfma_f32_16x16x32_bf16 v[112:115], v[140:143], v[196:199], v[112:115]
	v_mfma_f32_16x16x32_bf16 v[96:99], v[148:151], v[196:199], v[96:99]
	v_mfma_f32_16x16x32_bf16 v[124:127], v[144:147], v[176:179], v[124:127]
	v_mfma_f32_16x16x32_bf16 v[108:111], v[152:155], v[176:179], v[108:111]
	v_mfma_f32_16x16x32_bf16 v[120:123], v[144:147], v[184:187], v[120:123]
	v_mfma_f32_16x16x32_bf16 v[104:107], v[152:155], v[184:187], v[104:107]
	v_mfma_f32_16x16x32_bf16 v[116:119], v[144:147], v[192:195], v[116:119]
	v_mfma_f32_16x16x32_bf16 v[100:103], v[152:155], v[192:195], v[100:103]
	v_mfma_f32_16x16x32_bf16 v[112:115], v[144:147], v[200:203], v[112:115]
	v_mfma_f32_16x16x32_bf16 v[96:99], v[152:155], v[200:203], v[96:99]
	s_setprio 0
	s_setprio 1
	v_mfma_f32_16x16x32_bf16 v[92:95], v[156:159], v[172:175], v[92:95]
	v_mfma_f32_16x16x32_bf16 v[76:79], v[164:167], v[172:175], v[76:79]
	v_mfma_f32_16x16x32_bf16 v[88:91], v[156:159], v[180:183], v[88:91]
	v_mfma_f32_16x16x32_bf16 v[72:75], v[164:167], v[180:183], v[72:75]
	v_mfma_f32_16x16x32_bf16 v[84:87], v[156:159], v[188:191], v[84:87]
	v_mfma_f32_16x16x32_bf16 v[68:71], v[164:167], v[188:191], v[68:71]
	v_mfma_f32_16x16x32_bf16 v[80:83], v[156:159], v[196:199], v[80:83]
	v_mfma_f32_16x16x32_bf16 v[64:67], v[164:167], v[196:199], v[64:67]
	v_mfma_f32_16x16x32_bf16 v[92:95], v[160:163], v[176:179], v[92:95]
	v_mfma_f32_16x16x32_bf16 v[76:79], v[168:171], v[176:179], v[76:79]
	v_mfma_f32_16x16x32_bf16 v[88:91], v[160:163], v[184:187], v[88:91]
	v_mfma_f32_16x16x32_bf16 v[72:75], v[168:171], v[184:187], v[72:75]
	v_mfma_f32_16x16x32_bf16 v[84:87], v[160:163], v[192:195], v[84:87]
	v_mfma_f32_16x16x32_bf16 v[68:71], v[168:171], v[192:195], v[68:71]
	v_mfma_f32_16x16x32_bf16 v[80:83], v[160:163], v[200:203], v[80:83]
	v_mfma_f32_16x16x32_bf16 v[64:67], v[168:171], v[200:203], v[64:67]
	s_setprio 0
	s_barrier
	s_add_i32 s30, s74, s54
	v_lshl_add_u64 v[204:205], v[204:205], 0, s[6:7]
	s_mov_b32 m0, s30
	ds_read_b128 v[172:175], v139 offset:49152
	ds_read_b128 v[176:179], v139 offset:50176
	ds_read_b128 v[180:183], v139 offset:51200
	ds_read_b128 v[184:187], v139 offset:52224
	ds_read_b128 v[188:191], v139 offset:53248
	ds_read_b128 v[192:195], v139 offset:54272
	ds_read_b128 v[196:199], v139 offset:55296
	ds_read_b128 v[200:203], v139 offset:56320
	global_load_lds_dwordx4 v[204:205], off
	s_add_i32 m0, s30, 0x2000
	s_add_u32 s30, s36, 0x100080
	v_lshl_add_u64 v[204:205], v[206:207], 0, s[6:7]
	s_addc_u32 s31, s37, 0
	s_add_i32 s36, s75, s54
	global_load_lds_dwordx4 v[204:205], off
	v_lshl_add_u64 v[204:205], s[30:31], 0, v[128:129]
	s_mov_b32 m0, s36
	s_nop 0
	global_load_lds_dwordx4 v[204:205], off
	v_lshl_add_u64 v[204:205], s[30:31], 0, v[130:131]
	s_add_i32 m0, s36, 0x2000
	s_nop 0
	global_load_lds_dwordx4 v[204:205], off
	v_lshl_add_u64 v[204:205], v[208:209], 0, s[6:7]
	s_mov_b32 m0, s61
	s_nop 0
	global_load_lds_dwordx4 v[204:205], off
	v_lshl_add_u64 v[204:205], v[210:211], 0, s[6:7]
	s_mov_b32 m0, s62
	s_nop 0
	global_load_lds_dwordx4 v[204:205], off
	s_waitcnt vmcnt(8)
	s_waitcnt lgkmcnt(0)
	s_barrier
	s_setprio 1
	s_waitcnt lgkmcnt(0)
	v_mfma_f32_16x16x32_bf16 v[60:63], v[140:143], v[172:175], v[60:63]
	v_mfma_f32_16x16x32_bf16 v[44:47], v[148:151], v[172:175], v[44:47]
	v_mfma_f32_16x16x32_bf16 v[56:59], v[140:143], v[180:183], v[56:59]
	v_mfma_f32_16x16x32_bf16 v[40:43], v[148:151], v[180:183], v[40:43]
	v_mfma_f32_16x16x32_bf16 v[52:55], v[140:143], v[188:191], v[52:55]
	v_mfma_f32_16x16x32_bf16 v[36:39], v[148:151], v[188:191], v[36:39]
	v_mfma_f32_16x16x32_bf16 v[48:51], v[140:143], v[196:199], v[48:51]
	v_mfma_f32_16x16x32_bf16 v[32:35], v[148:151], v[196:199], v[32:35]
	v_mfma_f32_16x16x32_bf16 v[60:63], v[144:147], v[176:179], v[60:63]
	v_mfma_f32_16x16x32_bf16 v[44:47], v[152:155], v[176:179], v[44:47]
	v_mfma_f32_16x16x32_bf16 v[56:59], v[144:147], v[184:187], v[56:59]
	v_mfma_f32_16x16x32_bf16 v[40:43], v[152:155], v[184:187], v[40:43]
	v_mfma_f32_16x16x32_bf16 v[52:55], v[144:147], v[192:195], v[52:55]
	v_mfma_f32_16x16x32_bf16 v[36:39], v[152:155], v[192:195], v[36:39]
	v_mfma_f32_16x16x32_bf16 v[48:51], v[144:147], v[200:203], v[48:51]
	v_mfma_f32_16x16x32_bf16 v[32:35], v[152:155], v[200:203], v[32:35]
	s_setprio 0
	s_setprio 1
	v_mfma_f32_16x16x32_bf16 v[28:31], v[156:159], v[172:175], v[28:31]
	v_mfma_f32_16x16x32_bf16 v[12:15], v[164:167], v[172:175], v[12:15]
	v_mfma_f32_16x16x32_bf16 v[24:27], v[156:159], v[180:183], v[24:27]
	v_mfma_f32_16x16x32_bf16 v[8:11], v[164:167], v[180:183], v[8:11]
	v_mfma_f32_16x16x32_bf16 v[20:23], v[156:159], v[188:191], v[20:23]
	v_mfma_f32_16x16x32_bf16 v[4:7], v[164:167], v[188:191], v[4:7]
	v_mfma_f32_16x16x32_bf16 v[16:19], v[156:159], v[196:199], v[16:19]
	v_mfma_f32_16x16x32_bf16 v[0:3], v[164:167], v[196:199], v[0:3]
	v_mfma_f32_16x16x32_bf16 v[28:31], v[160:163], v[176:179], v[28:31]
	v_mfma_f32_16x16x32_bf16 v[12:15], v[168:171], v[176:179], v[12:15]
	v_mfma_f32_16x16x32_bf16 v[24:27], v[160:163], v[184:187], v[24:27]
	v_mfma_f32_16x16x32_bf16 v[8:11], v[168:171], v[184:187], v[8:11]
	v_mfma_f32_16x16x32_bf16 v[20:23], v[160:163], v[192:195], v[20:23]
	v_mfma_f32_16x16x32_bf16 v[4:7], v[168:171], v[192:195], v[4:7]
	v_mfma_f32_16x16x32_bf16 v[16:19], v[160:163], v[200:203], v[16:19]
	v_mfma_f32_16x16x32_bf16 v[0:3], v[168:171], v[200:203], v[0:3]
	s_setprio 0
	s_barrier
	s_add_u32 s71, s71, 0x100
	s_addc_u32 s72, s72, 0
	s_cmp_ge_u32 s73, s67
	s_mov_b64 s[30:31], s[34:35]
	s_mov_b32 s36, s73
	s_cbranch_scc0 .LBB0_1859
	s_andn2_b64 vcc, exec, s[48:49]
	s_cbranch_vccnz .LBB0_1851
	v_mov_b32_e32 v0, 0
	s_mov_b32 s64, s22
	s_mov_b32 s63, s24
	s_mov_b64 s[18:19], s[28:29]
	s_mov_b64 s[20:21], s[26:27]
	s_mov_b32 s65, s66
	v_mov_b32_e32 v1, v0
	v_mov_b64_e32 v[2:3], v[0:1]
	v_mov_b64_e32 v[16:17], v[0:1]
	v_mov_b64_e32 v[18:19], v[0:1]
	v_mov_b64_e32 v[4:5], v[0:1]
	v_mov_b64_e32 v[6:7], v[0:1]
	v_mov_b64_e32 v[20:21], v[0:1]
	v_mov_b64_e32 v[22:23], v[0:1]
	v_mov_b64_e32 v[8:9], v[0:1]
	v_mov_b64_e32 v[10:11], v[0:1]
	v_mov_b64_e32 v[24:25], v[0:1]
	v_mov_b64_e32 v[26:27], v[0:1]
	v_mov_b64_e32 v[12:13], v[0:1]
	v_mov_b64_e32 v[14:15], v[0:1]
	v_mov_b64_e32 v[28:29], v[0:1]
	v_mov_b64_e32 v[30:31], v[0:1]
	v_mov_b64_e32 v[32:33], v[0:1]
	v_mov_b64_e32 v[34:35], v[0:1]
	v_mov_b64_e32 v[48:49], v[0:1]
	v_mov_b64_e32 v[50:51], v[0:1]
	v_mov_b64_e32 v[36:37], v[0:1]
	v_mov_b64_e32 v[38:39], v[0:1]
	v_mov_b64_e32 v[52:53], v[0:1]
	v_mov_b64_e32 v[54:55], v[0:1]
	v_mov_b64_e32 v[40:41], v[0:1]
	v_mov_b64_e32 v[42:43], v[0:1]
	v_mov_b64_e32 v[56:57], v[0:1]
	v_mov_b64_e32 v[58:59], v[0:1]
	v_mov_b64_e32 v[44:45], v[0:1]
	v_mov_b64_e32 v[46:47], v[0:1]
	v_mov_b64_e32 v[60:61], v[0:1]
	v_mov_b64_e32 v[62:63], v[0:1]
	v_mov_b64_e32 v[64:65], v[0:1]
	v_mov_b64_e32 v[66:67], v[0:1]
	v_mov_b64_e32 v[80:81], v[0:1]
	v_mov_b64_e32 v[82:83], v[0:1]
	v_mov_b64_e32 v[68:69], v[0:1]
	v_mov_b64_e32 v[70:71], v[0:1]
	v_mov_b64_e32 v[84:85], v[0:1]
	v_mov_b64_e32 v[86:87], v[0:1]
	v_mov_b64_e32 v[72:73], v[0:1]
	v_mov_b64_e32 v[74:75], v[0:1]
	v_mov_b64_e32 v[88:89], v[0:1]
	v_mov_b64_e32 v[90:91], v[0:1]
	v_mov_b64_e32 v[76:77], v[0:1]
	v_mov_b64_e32 v[78:79], v[0:1]
	v_mov_b64_e32 v[92:93], v[0:1]
	v_mov_b64_e32 v[94:95], v[0:1]
	v_mov_b64_e32 v[96:97], v[0:1]
	v_mov_b64_e32 v[98:99], v[0:1]
	v_mov_b64_e32 v[112:113], v[0:1]
	v_mov_b64_e32 v[114:115], v[0:1]
	v_mov_b64_e32 v[100:101], v[0:1]
	v_mov_b64_e32 v[102:103], v[0:1]
	v_mov_b64_e32 v[116:117], v[0:1]
	v_mov_b64_e32 v[118:119], v[0:1]
	v_mov_b64_e32 v[104:105], v[0:1]
	v_mov_b64_e32 v[106:107], v[0:1]
	v_mov_b64_e32 v[120:121], v[0:1]
	v_mov_b64_e32 v[122:123], v[0:1]
	v_mov_b64_e32 v[108:109], v[0:1]
	v_mov_b64_e32 v[110:111], v[0:1]
	v_mov_b64_e32 v[124:125], v[0:1]
	v_mov_b64_e32 v[126:127], v[0:1]
	s_branch .LBB0_1851
